# one static s_setprio 1 for waves 4-7 on entry to the mixer-B and mixer-C (MLA) tile loops, reset at loop exit (asm guide 6.3 form); nothing else changed
# speedup vs baseline: 1.0023x; 1.0023x over previous
.Lb_fast:
	s_cmp_lt_u32 s77, 0x100
	s_cbranch_scc1 .Lprio_b_done
	s_setprio 1

.Lb_exit:
	s_setprio 0
	s_nop 15
	s_branch .LBB0_174

.LBB0_204:
	s_or_b64 exec, exec, s[8:9]
	s_waitcnt vmcnt(0)
	v_lshlrev_b32_e32 v102, 16, v78
	v_and_b32_e32 v103, 0xffff0000, v78
	s_mov_b32 s8, 0x3e16c740
	v_lshlrev_b32_e32 v78, 16, v79
	v_and_b32_e32 v79, 0xffff0000, v79
	v_lshlrev_b32_e32 v104, 16, v80
	v_and_b32_e32 v105, 0xffff0000, v80
	v_lshlrev_b32_e32 v80, 16, v81
	v_and_b32_e32 v81, 0xffff0000, v81
	v_pk_mul_f32 v[78:79], v[78:79], s[8:9] op_sel_hi:[1,0]
	v_pk_mul_f32 v[80:81], v[80:81], s[8:9] op_sel_hi:[1,0]
	v_cvt_pk_bf16_f32 v139, v78, v79
	v_cvt_pk_bf16_f32 v141, v80, v81
	v_lshlrev_b32_e32 v78, 16, v74
	v_and_b32_e32 v79, 0xffff0000, v74
	v_lshlrev_b32_e32 v74, 16, v75
	v_and_b32_e32 v75, 0xffff0000, v75
	v_lshlrev_b32_e32 v80, 16, v76
	v_and_b32_e32 v81, 0xffff0000, v76
	v_lshlrev_b32_e32 v76, 16, v77
	v_and_b32_e32 v77, 0xffff0000, v77
	v_pk_mul_f32 v[74:75], v[74:75], s[8:9] op_sel_hi:[1,0]
	v_pk_mul_f32 v[76:77], v[76:77], s[8:9] op_sel_hi:[1,0]
	v_cvt_pk_bf16_f32 v143, v74, v75
	v_cvt_pk_bf16_f32 v145, v76, v77
	v_lshlrev_b32_e32 v74, 16, v70
	v_and_b32_e32 v75, 0xffff0000, v70
	v_lshlrev_b32_e32 v70, 16, v71
	v_and_b32_e32 v71, 0xffff0000, v71
	v_lshlrev_b32_e32 v76, 16, v72
	v_and_b32_e32 v77, 0xffff0000, v72
	v_lshlrev_b32_e32 v72, 16, v73
	v_and_b32_e32 v73, 0xffff0000, v73
	v_pk_mul_f32 v[70:71], v[70:71], s[8:9] op_sel_hi:[1,0]
	v_pk_mul_f32 v[72:73], v[72:73], s[8:9] op_sel_hi:[1,0]
	v_cvt_pk_bf16_f32 v151, v70, v71
	v_cvt_pk_bf16_f32 v153, v72, v73
	v_lshlrev_b32_e32 v70, 16, v66
	v_and_b32_e32 v71, 0xffff0000, v66
	v_lshlrev_b32_e32 v66, 16, v67
	v_and_b32_e32 v67, 0xffff0000, v67
	v_lshlrev_b32_e32 v72, 16, v68
	v_and_b32_e32 v73, 0xffff0000, v68
	v_lshlrev_b32_e32 v68, 16, v69
	v_and_b32_e32 v69, 0xffff0000, v69
	v_pk_mul_f32 v[70:71], v[70:71], s[8:9] op_sel_hi:[1,0]
	v_pk_mul_f32 v[66:67], v[66:67], s[8:9] op_sel_hi:[1,0]
	v_pk_mul_f32 v[68:69], v[68:69], s[8:9] op_sel_hi:[1,0]
	v_pk_mul_f32 v[74:75], v[74:75], s[8:9] op_sel_hi:[1,0]
	v_pk_mul_f32 v[72:73], v[72:73], s[8:9] op_sel_hi:[1,0]
	v_cvt_pk_bf16_f32 v154, v70, v71
	v_cvt_pk_bf16_f32 v155, v66, v67
	v_cvt_pk_bf16_f32 v157, v68, v69
	v_lshlrev_b32_e32 v66, 16, v50
	v_and_b32_e32 v67, 0xffff0000, v46
	v_and_b32_e32 v69, 0xffff0000, v50
	v_mov_b32_e32 v70, v62
	v_mov_b32_e32 v71, v65
	v_mov_b32_e32 v95, v64
	v_cvt_pk_bf16_f32 v150, v74, v75
	v_cvt_pk_bf16_f32 v156, v72, v73
	v_pk_mul_f32 v[70:71], v[70:71], v[66:67]
	v_mov_b32_e32 v73, v64
	v_mov_b32_e32 v75, v67
	v_mov_b32_e32 v64, v63
	v_mov_b32_e32 v67, v69
	v_mov_b32_e32 v94, v63
	v_lshlrev_b32_e32 v68, 16, v46
	v_mov_b32_e32 v72, v62
	v_pk_mul_f32 v[62:63], v[64:65], v[66:67]
	v_lshlrev_b32_e32 v64, 16, v51
	v_and_b32_e32 v65, 0xffff0000, v47
	v_lshlrev_b32_e32 v46, 16, v47
	v_and_b32_e32 v47, 0xffff0000, v51
	v_mov_b32_e32 v50, v58
	v_mov_b32_e32 v51, v61
	v_mov_b32_e32 v96, v59
	v_mov_b32_e32 v97, v60
	v_pk_fma_f32 v[70:71], v[94:95], v[68:69], v[70:71]
	v_pk_mul_f32 v[50:51], v[50:51], v[64:65]
	v_mov_b32_e32 v67, v60
	v_mov_b32_e32 v69, v65
	v_mov_b32_e32 v60, v59
	v_mov_b32_e32 v65, v47
	v_mov_b32_e32 v74, v68
	v_pk_fma_f32 v[50:51], v[96:97], v[46:47], v[50:51]
	v_mov_b32_e32 v66, v58
	v_mov_b32_e32 v68, v46
	v_pk_mul_f32 v[46:47], v[60:61], v[64:65]
	v_and_b32_e32 v59, 0xffff0000, v52
	v_pk_fma_f32 v[46:47], v[66:67], v[68:69], v[46:47] neg_lo:[0,0,1] neg_hi:[0,0,1]
	v_mov_b32_e32 v60, v54
	v_pk_mul_f32 v[46:47], v[46:47], s[8:9] op_sel_hi:[1,0]
	v_mov_b32_e32 v61, v57
	v_cvt_pk_bf16_f32 v147, v46, v47
	v_pk_mul_f32 v[46:47], v[50:51], s[8:9] op_sel_hi:[1,0]
	v_lshlrev_b32_e32 v50, 16, v52
	v_and_b32_e32 v51, 0xffff0000, v48
	v_mov_b32_e32 v98, v55
	v_mov_b32_e32 v99, v56
	v_lshlrev_b32_e32 v58, 16, v48
	v_pk_mul_f32 v[60:61], v[60:61], v[50:51]
	v_mov_b32_e32 v64, v54
	v_mov_b32_e32 v65, v56
	v_mov_b32_e32 v67, v51
	v_mov_b32_e32 v56, v55
	v_mov_b32_e32 v51, v59
	v_lshlrev_b32_e32 v54, 16, v53
	v_and_b32_e32 v55, 0xffff0000, v49
	v_lshlrev_b32_e32 v48, 16, v49
	v_and_b32_e32 v49, 0xffff0000, v53
	v_mov_b32_e32 v52, v42
	v_mov_b32_e32 v53, v45
	v_mov_b32_e32 v101, v44
	v_pk_fma_f32 v[60:61], v[98:99], v[58:59], v[60:61]
	v_mov_b32_e32 v66, v58
	v_pk_mul_f32 v[50:51], v[56:57], v[50:51]
	v_pk_mul_f32 v[52:53], v[52:53], v[54:55]
	v_mov_b32_e32 v57, v44
	v_mov_b32_e32 v59, v55
	v_mov_b32_e32 v44, v43
	v_mov_b32_e32 v55, v49
	v_mov_b32_e32 v100, v43
	v_pk_fma_f32 v[50:51], v[64:65], v[66:67], v[50:51] neg_lo:[0,0,1] neg_hi:[0,0,1]
	v_mov_b32_e32 v56, v42
	v_mov_b32_e32 v58, v48
	v_pk_mul_f32 v[42:43], v[44:45], v[54:55]
	v_pk_mul_f32 v[50:51], v[50:51], s[8:9] op_sel_hi:[1,0]
	v_pk_fma_f32 v[42:43], v[56:57], v[58:59], v[42:43] neg_lo:[0,0,1] neg_hi:[0,0,1]
	v_cvt_pk_bf16_f32 v148, v50, v51
	v_pk_mul_f32 v[50:51], v[60:61], s[8:9] op_sel_hi:[1,0]
	v_pk_fma_f32 v[52:53], v[100:101], v[48:49], v[52:53]
	v_pk_mul_f32 v[42:43], v[42:43], s[8:9] op_sel_hi:[1,0]
	v_cvt_pk_bf16_f32 v160, v50, v51
	v_cvt_pk_bf16_f32 v149, v42, v43
	v_pk_mul_f32 v[42:43], v[52:53], s[8:9] op_sel_hi:[1,0]
	v_lshlrev_b32_e32 v50, 16, v38
	v_and_b32_e32 v51, 0xffff0000, v38
	v_lshlrev_b32_e32 v38, 16, v39
	v_and_b32_e32 v39, 0xffff0000, v39
	v_lshlrev_b32_e32 v52, 16, v40
	v_and_b32_e32 v53, 0xffff0000, v40
	v_lshlrev_b32_e32 v40, 16, v41
	v_and_b32_e32 v41, 0xffff0000, v41
	v_pk_mul_f32 v[38:39], v[38:39], s[8:9] op_sel_hi:[1,0]
	v_pk_mul_f32 v[40:41], v[40:41], s[8:9] op_sel_hi:[1,0]
	v_cvt_pk_bf16_f32 v115, v38, v39
	v_cvt_pk_bf16_f32 v117, v40, v41
	v_lshlrev_b32_e32 v38, 16, v34
	v_and_b32_e32 v39, 0xffff0000, v34
	v_lshlrev_b32_e32 v34, 16, v35
	v_and_b32_e32 v35, 0xffff0000, v35
	v_lshlrev_b32_e32 v40, 16, v36
	v_and_b32_e32 v41, 0xffff0000, v36
	v_lshlrev_b32_e32 v36, 16, v37
	v_and_b32_e32 v37, 0xffff0000, v37
	v_pk_mul_f32 v[34:35], v[34:35], s[8:9] op_sel_hi:[1,0]
	v_pk_mul_f32 v[36:37], v[36:37], s[8:9] op_sel_hi:[1,0]
	v_cvt_pk_bf16_f32 v131, v34, v35
	v_cvt_pk_bf16_f32 v133, v36, v37
	v_lshlrev_b32_e32 v34, 16, v30
	v_and_b32_e32 v35, 0xffff0000, v30
	v_lshlrev_b32_e32 v30, 16, v31
	v_and_b32_e32 v31, 0xffff0000, v31
	v_lshlrev_b32_e32 v36, 16, v32
	v_and_b32_e32 v37, 0xffff0000, v32
	v_lshlrev_b32_e32 v32, 16, v33
	v_and_b32_e32 v33, 0xffff0000, v33
	v_pk_mul_f32 v[30:31], v[30:31], s[8:9] op_sel_hi:[1,0]
	v_pk_mul_f32 v[32:33], v[32:33], s[8:9] op_sel_hi:[1,0]
	v_cvt_pk_bf16_f32 v127, v30, v31
	v_cvt_pk_bf16_f32 v129, v32, v33
	v_lshlrev_b32_e32 v30, 16, v26
	v_and_b32_e32 v31, 0xffff0000, v26
	v_lshlrev_b32_e32 v26, 16, v27
	v_and_b32_e32 v27, 0xffff0000, v27
	v_lshlrev_b32_e32 v32, 16, v28
	v_and_b32_e32 v33, 0xffff0000, v28
	v_lshlrev_b32_e32 v28, 16, v29
	v_and_b32_e32 v29, 0xffff0000, v29
	v_pk_mul_f32 v[30:31], v[30:31], s[8:9] op_sel_hi:[1,0]
	v_pk_mul_f32 v[26:27], v[26:27], s[8:9] op_sel_hi:[1,0]
	v_pk_mul_f32 v[28:29], v[28:29], s[8:9] op_sel_hi:[1,0]
	v_pk_mul_f32 v[34:35], v[34:35], s[8:9] op_sel_hi:[1,0]
	v_pk_mul_f32 v[32:33], v[32:33], s[8:9] op_sel_hi:[1,0]
	v_cvt_pk_bf16_f32 v118, v30, v31
	v_cvt_pk_bf16_f32 v119, v26, v27
	v_cvt_pk_bf16_f32 v121, v28, v29
	v_lshlrev_b32_e32 v26, 16, v10
	v_and_b32_e32 v27, 0xffff0000, v6
	v_and_b32_e32 v29, 0xffff0000, v10
	v_mov_b32_e32 v30, v22
	v_mov_b32_e32 v31, v25
	v_cvt_pk_bf16_f32 v161, v42, v43
	v_mov_b32_e32 v43, v24
	v_cvt_pk_bf16_f32 v126, v34, v35
	v_cvt_pk_bf16_f32 v120, v32, v33
	v_pk_mul_f32 v[30:31], v[30:31], v[26:27]
	v_mov_b32_e32 v33, v24
	v_mov_b32_e32 v35, v27
	v_mov_b32_e32 v24, v23
	v_mov_b32_e32 v27, v29
	v_mov_b32_e32 v42, v23
	v_lshlrev_b32_e32 v28, 16, v6
	v_mov_b32_e32 v32, v22
	v_pk_mul_f32 v[22:23], v[24:25], v[26:27]
	v_lshlrev_b32_e32 v24, 16, v11
	v_and_b32_e32 v25, 0xffff0000, v7
	v_lshlrev_b32_e32 v6, 16, v7
	v_and_b32_e32 v7, 0xffff0000, v11
	v_mov_b32_e32 v10, v18
	v_mov_b32_e32 v11, v21
	v_mov_b32_e32 v44, v19
	v_mov_b32_e32 v45, v20
	v_pk_fma_f32 v[30:31], v[42:43], v[28:29], v[30:31]
	v_pk_mul_f32 v[10:11], v[10:11], v[24:25]
	v_mov_b32_e32 v27, v20
	v_mov_b32_e32 v29, v25
	v_mov_b32_e32 v20, v19
	v_mov_b32_e32 v25, v7
	v_mov_b32_e32 v34, v28
	v_pk_fma_f32 v[10:11], v[44:45], v[6:7], v[10:11]
	v_mov_b32_e32 v26, v18
	v_mov_b32_e32 v28, v6
	v_pk_mul_f32 v[6:7], v[20:21], v[24:25]
	v_and_b32_e32 v19, 0xffff0000, v12
	v_pk_fma_f32 v[6:7], v[26:27], v[28:29], v[6:7] neg_lo:[0,0,1] neg_hi:[0,0,1]
	v_mov_b32_e32 v20, v14
	v_pk_mul_f32 v[6:7], v[6:7], s[8:9] op_sel_hi:[1,0]
	v_mov_b32_e32 v21, v17
	v_cvt_pk_bf16_f32 v123, v6, v7
	v_pk_mul_f32 v[6:7], v[10:11], s[8:9] op_sel_hi:[1,0]
	v_lshlrev_b32_e32 v10, 16, v12
	v_and_b32_e32 v11, 0xffff0000, v8
	v_cvt_pk_bf16_f32 v159, v46, v47
	v_mov_b32_e32 v46, v15
	v_mov_b32_e32 v47, v16
	v_lshlrev_b32_e32 v18, 16, v8
	v_pk_mul_f32 v[20:21], v[20:21], v[10:11]
	v_mov_b32_e32 v24, v14
	v_mov_b32_e32 v25, v16
	v_mov_b32_e32 v27, v11
	v_mov_b32_e32 v16, v15
	v_mov_b32_e32 v11, v19
	v_lshlrev_b32_e32 v14, 16, v13
	v_and_b32_e32 v15, 0xffff0000, v9
	v_lshlrev_b32_e32 v8, 16, v9
	v_and_b32_e32 v9, 0xffff0000, v13
	v_mov_b32_e32 v12, v2
	v_mov_b32_e32 v13, v5
	v_mov_b32_e32 v49, v4
	v_pk_fma_f32 v[20:21], v[46:47], v[18:19], v[20:21]
	v_pk_mul_f32 v[10:11], v[16:17], v[10:11]
	v_pk_mul_f32 v[12:13], v[12:13], v[14:15]
	v_mov_b32_e32 v17, v4
	v_mov_b32_e32 v19, v15
	v_mov_b32_e32 v4, v3
	v_mov_b32_e32 v15, v9
	v_mov_b32_e32 v48, v3
	v_mov_b32_e32 v26, v18
	v_mov_b32_e32 v16, v2
	v_mov_b32_e32 v18, v8
	v_pk_mul_f32 v[2:3], v[4:5], v[14:15]
	v_pk_fma_f32 v[12:13], v[48:49], v[8:9], v[12:13]
	v_pk_fma_f32 v[2:3], v[16:17], v[18:19], v[2:3] neg_lo:[0,0,1] neg_hi:[0,0,1]
	v_and_b32_e32 v0, 19, v88
	v_pk_mul_f32 v[2:3], v[2:3], s[8:9] op_sel_hi:[1,0]
	v_cvt_pk_bf16_f32 v135, v6, v7
	v_cvt_pk_bf16_f32 v125, v2, v3
	v_pk_mul_f32 v[2:3], v[12:13], s[8:9] op_sel_hi:[1,0]
	v_pk_fma_f32 v[62:63], v[72:73], v[74:75], v[62:63] neg_lo:[0,0,1] neg_hi:[0,0,1]
	v_cvt_pk_bf16_f32 v137, v2, v3
	v_lshlrev_b32_e32 v2, 1, v88
	v_lshrrev_b32_e32 v3, 1, v89
	v_and_b32_e32 v2, 8, v2
	v_and_b32_e32 v4, 4, v3
	v_or3_b32 v0, v2, v0, v4
	v_lshlrev_b32_e32 v2, 6, v0
	v_lshrrev_b32_e32 v4, 2, v0
	v_lshlrev_b32_e32 v5, 7, v0
	v_lshrrev_b32_e32 v0, 1, v0
	v_bitop3_b32 v6, v0, v86, 7 bitop3:0x6c
	v_lshl_or_b32 v246, v6, 4, v5
	v_or_b32_e32 v6, 2, v86
	v_bitop3_b32 v7, v0, v6, 7 bitop3:0x6c
	v_lshl_or_b32 v247, v7, 4, v5
	v_or_b32_e32 v7, 4, v86
	v_bitop3_b32 v7, v0, v7, 7 bitop3:0x6c
	v_pk_fma_f32 v[22:23], v[32:33], v[34:35], v[22:23] neg_lo:[0,0,1] neg_hi:[0,0,1]
	v_pk_fma_f32 v[10:11], v[24:25], v[26:27], v[10:11] neg_lo:[0,0,1] neg_hi:[0,0,1]
	v_lshl_or_b32 v244, v7, 4, v5
	v_or_b32_e32 v7, 6, v86
	v_pk_mul_f32 v[62:63], v[62:63], s[8:9] op_sel_hi:[1,0]
	v_pk_mul_f32 v[22:23], v[22:23], s[8:9] op_sel_hi:[1,0]
	v_pk_mul_f32 v[10:11], v[10:11], s[8:9] op_sel_hi:[1,0]
	v_bitop3_b32 v0, v0, v7, 7 bitop3:0x6c
	v_pk_mul_f32 v[102:103], v[102:103], s[8:9] op_sel_hi:[1,0]
	v_pk_mul_f32 v[104:105], v[104:105], s[8:9] op_sel_hi:[1,0]
	v_pk_mul_f32 v[78:79], v[78:79], s[8:9] op_sel_hi:[1,0]
	v_pk_mul_f32 v[80:81], v[80:81], s[8:9] op_sel_hi:[1,0]
	v_pk_mul_f32 v[76:77], v[76:77], s[8:9] op_sel_hi:[1,0]
	v_cvt_pk_bf16_f32 v146, v62, v63
	v_pk_mul_f32 v[62:63], v[70:71], s[8:9] op_sel_hi:[1,0]
	v_pk_mul_f32 v[50:51], v[50:51], s[8:9] op_sel_hi:[1,0]
	v_pk_mul_f32 v[52:53], v[52:53], s[8:9] op_sel_hi:[1,0]
	v_pk_mul_f32 v[38:39], v[38:39], s[8:9] op_sel_hi:[1,0]
	v_pk_mul_f32 v[40:41], v[40:41], s[8:9] op_sel_hi:[1,0]
	v_pk_mul_f32 v[36:37], v[36:37], s[8:9] op_sel_hi:[1,0]
	v_cvt_pk_bf16_f32 v122, v22, v23
	v_pk_mul_f32 v[22:23], v[30:31], s[8:9] op_sel_hi:[1,0]
	v_cvt_pk_bf16_f32 v124, v10, v11
	v_pk_mul_f32 v[10:11], v[20:21], s[8:9] op_sel_hi:[1,0]
	v_lshl_or_b32 v243, v0, 4, v5
	v_bitop3_b32 v0, v4, v86, 3 bitop3:0x6c
	v_bitop3_b32 v4, v4, v6, 3 bitop3:0x6c
	s_lshl_b32 s9, s18, 8
	v_readlane_b32 s18, v254, 41
	v_lshlrev_b32_e32 v5, 7, v87
	v_bitop3_b32 v3, v3, v86, 7 bitop3:0x6c
	v_lshl_or_b32 v242, v4, 4, v2
	s_add_i32 s9, s18, s9
	v_add_u32_e32 v4, v92, v91
	s_movk_i32 s5, 0x1080
	v_lshl_or_b32 v245, v0, 4, v2
	v_lshl_or_b32 v241, v3, 4, v5
	s_add_i32 s9, s9, s31
	v_mad_i64_i32 v[2:3], s[20:21], v4, s5, 0
	v_mov_b32_e32 v0, 0x1080
	v_mad_i64_i32 v[2:3], s[20:21], s9, v0, v[2:3]
	v_lshlrev_b32_e32 v0, 4, v90
	v_and_b32_e32 v0, 0x70, v0
	v_readlane_b32 s20, v254, 38
	v_or_b32_e32 v2, v2, v0
	v_readlane_b32 s21, v254, 39
	v_bfe_u32 v6, v89, 1, 3
	v_bitop3_b32 v7, v86, v6, 2 bitop3:0x36
	v_lshl_add_u64 v[204:205], s[20:21], 0, v[2:3]
	v_lshl_add_u64 v[2:3], v[82:83], 0, s[0:1]
	v_readlane_b32 s0, v254, 42
	v_lshl_add_u64 v[2:3], v[84:85], 1, v[2:3]
	v_readlane_b32 s1, v254, 43
	v_bitop3_b32 v8, v86, v6, 4 bitop3:0x36
	v_bitop3_b32 v6, v86, v6, 6 bitop3:0x36
	v_lshl_add_u64 v[206:207], s[0:1], 0, v[2:3]
	s_add_u32 s0, s25, s24
	s_addc_u32 s1, 0, s19
	v_mov_b64_e32 v[2:3], s[0:1]
	s_movk_i32 s0, 0x280
	v_mad_i64_i32 v[2:3], s[0:1], v4, s0, v[2:3]
	v_readlane_b32 s0, v254, 44
	v_lshl_add_u64 v[2:3], v[2:3], 0, v[0:1]
	v_readlane_b32 s1, v254, 45
	v_mov_b32_e32 v16, v1
	v_mov_b32_e32 v17, v1
	v_cvt_pk_bf16_f32 v158, v62, v63
	v_cvt_pk_bf16_f32 v114, v50, v51
	v_cvt_pk_bf16_f32 v116, v52, v53
	v_cvt_pk_bf16_f32 v130, v38, v39
	v_cvt_pk_bf16_f32 v132, v40, v41
	v_cvt_pk_bf16_f32 v128, v36, v37
	v_cvt_pk_bf16_f32 v134, v22, v23
	v_cvt_pk_bf16_f32 v136, v10, v11
	v_lshl_or_b32 v240, v7, 4, v5
	v_lshl_or_b32 v215, v8, 4, v5
	v_lshl_or_b32 v214, v6, 4, v5
	v_lshl_add_u64 v[208:209], s[0:1], 0, v[2:3]
	v_mov_b32_e32 v0, v1
	v_mov_b32_e32 v2, v1
	v_mov_b32_e32 v3, v1
	v_mov_b32_e32 v4, v1
	v_mov_b32_e32 v5, v1
	v_mov_b32_e32 v6, v1
	v_mov_b32_e32 v7, v1
	v_mov_b32_e32 v8, v1
	v_mov_b32_e32 v9, v1
	v_mov_b32_e32 v10, v1
	v_mov_b32_e32 v11, v1
	v_mov_b32_e32 v12, v1
	v_mov_b32_e32 v13, v1
	v_mov_b32_e32 v14, v1
	v_mov_b32_e32 v15, v1
	v_bfrev_b32_e32 v82, 1
	v_mov_b64_e32 v[32:33], v[16:17]
	v_mov_b64_e32 v[48:49], v[16:17]
	v_mov_b64_e32 v[64:65], v[16:17]
	v_cvt_pk_bf16_f32 v138, v102, v103
	v_cvt_pk_bf16_f32 v140, v104, v105
	v_cvt_pk_bf16_f32 v142, v78, v79
	v_cvt_pk_bf16_f32 v144, v80, v81
	v_cvt_pk_bf16_f32 v152, v76, v77
	s_mov_b32 s8, 2
	s_mov_b32 s9, 0
	v_mov_b32_e32 v216, 0
	v_mov_b64_e32 v[30:31], v[14:15]
	v_mov_b64_e32 v[28:29], v[12:13]
	v_mov_b64_e32 v[26:27], v[10:11]
	v_mov_b64_e32 v[24:25], v[8:9]
	v_mov_b64_e32 v[22:23], v[6:7]
	v_mov_b64_e32 v[20:21], v[4:5]
	v_mov_b64_e32 v[18:19], v[2:3]
	v_mov_b64_e32 v[46:47], v[14:15]
	v_mov_b64_e32 v[44:45], v[12:13]
	v_mov_b64_e32 v[42:43], v[10:11]
	v_mov_b64_e32 v[40:41], v[8:9]
	v_mov_b64_e32 v[38:39], v[6:7]
	v_mov_b64_e32 v[36:37], v[4:5]
	v_mov_b64_e32 v[34:35], v[2:3]
	v_mov_b64_e32 v[62:63], v[14:15]
	v_mov_b64_e32 v[60:61], v[12:13]
	v_mov_b64_e32 v[58:59], v[10:11]
	v_mov_b64_e32 v[56:57], v[8:9]
	v_mov_b64_e32 v[54:55], v[6:7]
	v_mov_b64_e32 v[52:53], v[4:5]
	v_mov_b64_e32 v[50:51], v[2:3]
	s_mov_b32 s20, 0
	v_mov_b64_e32 v[202:203], v[0:1]
	v_mov_b32_e32 v83, v82
	v_mov_b32_e32 v84, v82
	v_mov_b32_e32 v85, v82
	v_mov_b32_e32 v86, v82
	v_mov_b32_e32 v87, v82
	v_mov_b32_e32 v88, v82
	v_mov_b32_e32 v89, v82
	v_mov_b32_e32 v90, v82
	v_mov_b32_e32 v91, v82
	v_mov_b32_e32 v92, v82
	v_mov_b32_e32 v93, v82
	v_mov_b32_e32 v94, v82
	v_mov_b32_e32 v95, v82
	v_mov_b32_e32 v96, v82
	v_mov_b32_e32 v97, v82
	s_cmp_lt_u32 s77, 0x100
	s_cbranch_scc1 .Lprio_c_done
	s_setprio 1
.Lprio_c_done:
	s_branch .LBB0_206
.LBB0_206:
	v_readlane_b32 s18, v253, 41
	v_readlane_b32 s19, v253, 42
	s_and_b64 vcc, exec, s[18:19]
	s_cbranch_vccz .Lc_w03
	s_waitcnt vmcnt(2)
	s_branch .Lc_bar

.Lc_resc_b3_ret:
	v_exp_f32_e32 v66, v66
	v_exp_f32_e32 v67, v67
	v_exp_f32_e32 v68, v68
	v_exp_f32_e32 v69, v69
	v_add_f32_e32 v212, v67, v66
	v_exp_f32_e32 v70, v70
	v_add_f32_e32 v212, v68, v212
	v_exp_f32_e32 v71, v71
	v_add_f32_e32 v212, v69, v212
	v_exp_f32_e32 v72, v72
	v_add_f32_e32 v212, v70, v212
	v_exp_f32_e32 v73, v73
	v_add_f32_e32 v212, v71, v212
	v_cvt_pk_bf16_f32 v66, v66, v67
	v_exp_f32_e32 v74, v74
	v_add_f32_e32 v212, v72, v212
	v_cvt_pk_bf16_f32 v67, v68, v69
	v_exp_f32_e32 v75, v75
	v_add_f32_e32 v212, v73, v212
	v_cvt_pk_bf16_f32 v68, v70, v71
	v_exp_f32_e32 v76, v76
	v_add_f32_e32 v212, v74, v212
	v_cvt_pk_bf16_f32 v69, v72, v73
	v_exp_f32_e32 v77, v77
	v_add_f32_e32 v212, v75, v212
	v_exp_f32_e32 v78, v78
	v_add_f32_e32 v212, v76, v212
	v_exp_f32_e32 v79, v79
	v_add_f32_e32 v212, v77, v212
	v_exp_f32_e32 v80, v80
	v_add_f32_e32 v212, v78, v212
	v_exp_f32_e32 v81, v81
	v_add_f32_e32 v212, v79, v212
	v_cvt_pk_bf16_f32 v70, v74, v75
	v_add_f32_e32 v212, v80, v212
	v_cvt_pk_bf16_f32 v71, v76, v77
	v_add_f32_e32 v212, v81, v212
	v_cvt_pk_bf16_f32 v72, v78, v79
	v_add_f32_e32 v202, v202, v212
	v_cvt_pk_bf16_f32 v73, v80, v81
	v_mfma_f32_32x32x16_bf16 v[18:33], v[162:165], v[66:69], v[18:33]
	s_add_i32 s0, s9, 1
	s_cmp_lg_u32 s9, 2
	s_cselect_b32 s9, s0, 0
	v_mfma_f32_32x32x16_bf16 v[2:17], v[170:173], v[66:69], v[2:17]
	s_add_i32 s0, s8, 1
	s_add_i32 s20, s20, 1
	s_cmp_lg_u32 s8, 2
	s_cselect_b32 s8, s0, 0
	s_mov_b64 s[0:1], 0x53000
	v_lshl_add_u64 v[206:207], v[206:207], 0, s[0:1]
	v_mfma_f32_32x32x16_bf16 v[18:33], v[174:177], v[70:73], v[18:33]
	s_mov_b64 s[0:1], 0xa000
	v_lshl_add_u64 v[204:205], v[204:205], 0, s[26:27]
	v_lshl_add_u64 v[208:209], v[208:209], 0, s[0:1]
	v_mfma_f32_32x32x16_bf16 v[2:17], v[178:181], v[70:73], v[2:17]
	s_cmp_eq_u32 s20, 31
	s_cbranch_scc0 .LBB0_206
	v_mov_b64_e32 v[66:67], v[82:83]
	v_mov_b64_e32 v[68:69], v[84:85]
	v_mov_b64_e32 v[70:71], v[86:87]
	v_mov_b64_e32 v[72:73], v[88:89]
	v_mov_b64_e32 v[74:75], v[90:91]
	v_mov_b64_e32 v[76:77], v[92:93]
	v_mov_b64_e32 v[78:79], v[94:95]
	v_mov_b64_e32 v[80:81], v[96:97]
	s_setprio 0
	s_branch .LBB0_223
